# RMSNorm row loops (ph0, N2/N3, final norm): counted vmcnt(12) per row when all 4 rows valid instead of waiting for all 16 loads before first row
# baseline (speedup 1.0000x reference)
; __device__ __forceinline__ float red64(float x) { x = red16(x); x += __shfl_xor(x, 16); x += __shfl_xor(x, 32); return x; }
;     ...
;     for (int r0 = gw; r0 < TT; r0 += 4 * nw) {
;         f32x4 v[4][4];
; #pragma unroll
;         for (int b = 0; b < 4; ++b) { const int r = r0 + b * nw;
;             if (r < TT) { const float* src = srcP ? (r < TP ? srcP + (size_t)r * DM : srcS + (size_t)(r - TP) * DM) : X + (size_t)r * DM;
; #pragma unroll
;                 for (int i = 0; i < 4; ++i) v[b][i] = *(const f32x4*)(src + i * 256 + lane * 4); } }
; #pragma unroll
;         for (int b = 0; b < 4; ++b) { const int r = r0 + b * nw;
;             if (r < TT) {
;                 float ss = 0.f;
; #pragma unroll
;                 for (int i = 0; i < 4; ++i) {
;                     if (nsl && r >= TP) {
;                         const float* s = scr + (size_t)(r - TP) * DM + i * 256 + lane * 4;
;                         for (int q = 0; q < nsl; ++q) v[b][i] = v[b][i] + *(const f32x4*)(s + (size_t)q * TS * DM);
;                         if (!final_inplace) *(f32x4*)(X + (size_t)r * DM + i * 256 + lane * 4) = v[b][i]; }
;                     ss += v[b][i][0] * v[b][i][0] + v[b][i][1] * v[b][i][1] + v[b][i][2] * v[b][i][2] + v[b][i][3] * v[b][i][3]; }
;                 ss = red64(ss);
;                 const float sc = rsqrtf(ss * (1.0f / DM) + EPS);
; #pragma unroll
;                 for (int i = 0; i < 4; ++i) {
;                     if (srcP && copy_x) *(f32x4*)(X + (size_t)r * DM + i * 256 + lane * 4) = v[b][i];
;                     f32x4 o = v[b][i] * sc * gv[i];
;                     if (final_inplace) *(f32x4*)(X + (size_t)r * DM + i * 256 + lane * 4) = o;
;                     else { u32x2 w; w.x = pkh(o[0], o[1]); w.y = pkh(o[2], o[3]); *(u32x2*)(XN + (size_t)r * DM + i * 256 + lane * 4) = w; }
;                 } } }
.LBB0_711:
	s_or_b64 exec, exec, s[4:5]
	s_and_b64 s[4:5], s[44:45], s[42:43]
	s_and_b64 s[4:5], s[4:5], s[40:41]
	s_xor_b64 s[4:5], s[4:5], exec
	s_cmp_eq_u64 s[4:5], 0
	s_cbranch_scc1 .Lnw_b
	s_waitcnt vmcnt(0)
.Lnw_b:
	s_waitcnt vmcnt(12)
	v_mul_f32_e32 v16, v79, v79
	v_mul_f32_e32 v100, v75, v75
	v_fmac_f32_e32 v16, v78, v78
	v_fmac_f32_e32 v100, v74, v74
	v_fmac_f32_e32 v16, v80, v80
	v_fmac_f32_e32 v100, v76, v76
	v_fmac_f32_e32 v16, v81, v81
	v_fmac_f32_e32 v100, v77, v77
	v_add_f32_e32 v16, v16, v100
	v_mul_f32_e32 v100, v71, v71
	v_fmac_f32_e32 v100, v70, v70
	v_fmac_f32_e32 v100, v72, v72
	v_fmac_f32_e32 v100, v73, v73
	v_pk_mul_f32 v[106:107], v[66:67], v[66:67]
	v_add_f32_e32 v16, v16, v100
	v_pk_mul_f32 v[100:101], v[68:69], v[68:69]
	v_add_f32_e32 v106, v106, v107
	v_add_f32_e32 v100, v100, v106
	v_add_f32_e32 v100, v101, v100
	v_add_f32_e32 v16, v16, v100
	s_nop 1
	v_add_f32_dpp v16, v16, v16 quad_perm:[1,0,3,2] row_mask:0xf bank_mask:0xf bound_ctrl:1
	s_nop 1
	v_add_f32_dpp v16, v16, v16 quad_perm:[2,3,0,1] row_mask:0xf bank_mask:0xf bound_ctrl:1
	s_nop 1
	v_add_f32_dpp v16, v16, v16 row_half_mirror row_mask:0xf bank_mask:0xf bound_ctrl:1
	s_nop 1
	v_add_f32_dpp v16, v16, v16 row_mirror row_mask:0xf bank_mask:0xf bound_ctrl:1
	ds_bpermute_b32 v100, v103, v16
	s_waitcnt lgkmcnt(0)
	v_add_f32_e32 v16, v16, v100
	ds_bpermute_b32 v100, v104, v16
	s_waitcnt lgkmcnt(0)
	v_add_f32_e32 v16, v16, v100
	v_fmamk_f32 v16, v16, 0x3a800000, v203
	v_mul_f32_e32 v100, 0x4b800000, v16
	v_cmp_gt_f32_e32 vcc, s16, v16
	s_nop 1
	v_cndmask_b32_e32 v16, v16, v100, vcc
	v_rsq_f32_e32 v16, v16
	s_nop 0
	v_mul_f32_e32 v100, 0x45800000, v16
	v_cndmask_b32_e32 v16, v16, v100, vcc
	v_pk_mul_f32 v[78:79], v[78:79], v[16:17] op_sel_hi:[1,0]
	v_pk_mul_f32 v[80:81], v[80:81], v[16:17] op_sel_hi:[1,0]
	v_pk_mul_f32 v[74:75], v[74:75], v[16:17] op_sel_hi:[1,0]
	v_pk_mul_f32 v[76:77], v[76:77], v[16:17] op_sel_hi:[1,0]
	v_pk_mul_f32 v[70:71], v[70:71], v[16:17] op_sel_hi:[1,0]
	v_pk_mul_f32 v[72:73], v[72:73], v[16:17] op_sel_hi:[1,0]
	v_pk_mul_f32 v[66:67], v[66:67], v[16:17] op_sel_hi:[1,0]
	v_pk_mul_f32 v[68:69], v[68:69], v[16:17] op_sel_hi:[1,0]
	v_pk_mul_f32 v[80:81], v[2:3], v[80:81]
	v_pk_mul_f32 v[78:79], v[0:1], v[78:79]
	v_pk_mul_f32 v[76:77], v[6:7], v[76:77]
	v_pk_mul_f32 v[74:75], v[4:5], v[74:75]
	v_pk_mul_f32 v[72:73], v[10:11], v[72:73]
	v_pk_mul_f32 v[70:71], v[8:9], v[70:71]
	v_pk_mul_f32 v[68:69], v[14:15], v[68:69]
	v_pk_mul_f32 v[66:67], v[12:13], v[66:67]
	global_store_dwordx4 v[98:99], v[78:81], off
	global_store_dwordx4 v[98:99], v[74:77], off offset:1024
	global_store_dwordx4 v[98:99], v[70:73], off offset:2048
	global_store_dwordx4 v[98:99], v[66:69], off offset:3072
	s_and_saveexec_b64 s[4:5], s[44:45]
	s_cbranch_execnz .LBB0_717
	s_or_b64 exec, exec, s[4:5]
	s_and_saveexec_b64 s[4:5], s[42:43]
	s_cbranch_execnz .LBB0_723

;     ...
;         for (int b = 0; b < 4; ++b) { const int r = r0 + b * nw;
;             if (r < TT) {
;                 float ss = 0.f;
; #pragma unroll
;                 for (int i = 0; i < 4; ++i) {
;                     if (nsl && r >= TP) {
;                         const float* s = scr + (size_t)(r - TP) * DM + i * 256 + lane * 4;
;                         for (int q = 0; q < nsl; ++q) v[b][i] = v[b][i] + *(const f32x4*)(s + (size_t)q * TS * DM);
;                         if (!final_inplace) *(f32x4*)(X + (size_t)r * DM + i * 256 + lane * 4) = v[b][i]; }
;                     ss += v[b][i][0] * v[b][i][0] + v[b][i][1] * v[b][i][1] + v[b][i][2] * v[b][i][2] + v[b][i][3] * v[b][i][3]; }
.LBB0_717:
	s_waitcnt vmcnt(12)
	v_add_u32_e32 v16, 0xffffc000, v105
	v_lshlrev_b64 v[66:67], 12, v[16:17]
	v_cmp_lt_i32_e64 s[44:45], s15, v105
	v_lshl_add_u64 v[66:67], v[82:83], 0, v[66:67]
	s_and_saveexec_b64 s[6:7], s[44:45]
	s_cbranch_execnz .LBB0_733
	s_or_b64 exec, exec, s[6:7]
	s_and_saveexec_b64 s[6:7], s[44:45]
	s_cbranch_execnz .LBB0_734

;     ...
;         for (int b = 0; b < 4; ++b) { const int r = r0 + b * nw;
;             if (r < TT) {
;                 float ss = 0.f;
; #pragma unroll
;                 for (int i = 0; i < 4; ++i) {
;                     if (nsl && r >= TP) {
;                         const float* s = scr + (size_t)(r - TP) * DM + i * 256 + lane * 4;
;                         for (int q = 0; q < nsl; ++q) v[b][i] = v[b][i] + *(const f32x4*)(s + (size_t)q * TS * DM);
;                         if (!final_inplace) *(f32x4*)(X + (size_t)r * DM + i * 256 + lane * 4) = v[b][i]; }
;                     ss += v[b][i][0] * v[b][i][0] + v[b][i][1] * v[b][i][1] + v[b][i][2] * v[b][i][2] + v[b][i][3] * v[b][i][3]; }
.LBB0_723:
	s_waitcnt vmcnt(12)
	v_add_u32_e32 v16, 0xffffc000, v94
	v_lshlrev_b64 v[66:67], 12, v[16:17]
	v_cmp_lt_i32_e64 s[42:43], s15, v94
	v_lshl_add_u64 v[66:67], v[82:83], 0, v[66:67]
	s_and_saveexec_b64 s[6:7], s[42:43]
	s_cbranch_execnz .LBB0_736
	s_or_b64 exec, exec, s[6:7]
	s_and_saveexec_b64 s[6:7], s[42:43]
	s_cbranch_execnz .LBB0_737

;     ...
;         for (int b = 0; b < 4; ++b) { const int r = r0 + b * nw;
;             if (r < TT) {
;                 float ss = 0.f;
; #pragma unroll
;                 for (int i = 0; i < 4; ++i) {
;                     if (nsl && r >= TP) {
;                         const float* s = scr + (size_t)(r - TP) * DM + i * 256 + lane * 4;
;                         for (int q = 0; q < nsl; ++q) v[b][i] = v[b][i] + *(const f32x4*)(s + (size_t)q * TS * DM);
;                         if (!final_inplace) *(f32x4*)(X + (size_t)r * DM + i * 256 + lane * 4) = v[b][i]; }
;                     ss += v[b][i][0] * v[b][i][0] + v[b][i][1] * v[b][i][1] + v[b][i][2] * v[b][i][2] + v[b][i][3] * v[b][i][3]; }
.LBB0_729:
	s_waitcnt vmcnt(12)
	v_add_u32_e32 v16, 0xffffc000, v92
	v_lshlrev_b64 v[66:67], 12, v[16:17]
	v_cmp_lt_i32_e64 s[40:41], s15, v92
	v_lshl_add_u64 v[66:67], v[82:83], 0, v[66:67]
	s_and_saveexec_b64 s[6:7], s[40:41]
	s_cbranch_execnz .LBB0_739
	s_or_b64 exec, exec, s[6:7]
	s_and_saveexec_b64 s[6:7], s[40:41]
	s_cbranch_execnz .LBB0_740

; __device__ __forceinline__ float red64(float x) { x = red16(x); x += __shfl_xor(x, 16); x += __shfl_xor(x, 32); return x; }
;     ...
;         for (int b = 0; b < 4; ++b) { const int r = r0 + b * nw;
;             if (r < TT) {
;                 float ss = 0.f;
; #pragma unroll
;                 for (int i = 0; i < 4; ++i) {
;                     if (nsl && r >= TP) {
;                         const float* s = scr + (size_t)(r - TP) * DM + i * 256 + lane * 4;
;                         for (int q = 0; q < nsl; ++q) v[b][i] = v[b][i] + *(const f32x4*)(s + (size_t)q * TS * DM);
;                         if (!final_inplace) *(f32x4*)(X + (size_t)r * DM + i * 256 + lane * 4) = v[b][i]; }
;                     ss += v[b][i][0] * v[b][i][0] + v[b][i][1] * v[b][i][1] + v[b][i][2] * v[b][i][2] + v[b][i][3] * v[b][i][3]; }
;                 ss = red64(ss);
;                 const float sc = rsqrtf(ss * (1.0f / DM) + EPS);
; #pragma unroll
;                 for (int i = 0; i < 4; ++i) {
;                     if (srcP && copy_x) *(f32x4*)(X + (size_t)r * DM + i * 256 + lane * 4) = v[b][i];
;                     f32x4 o = v[b][i] * sc * gv[i];
;                     if (final_inplace) *(f32x4*)(X + (size_t)r * DM + i * 256 + lane * 4) = o;
;                     else { u32x2 w; w.x = pkh(o[0], o[1]); w.y = pkh(o[2], o[3]); *(u32x2*)(XN + (size_t)r * DM + i * 256 + lane * 4) = w; }
;                 } } }
.Lnw_a:
	s_waitcnt vmcnt(12)
	v_mul_f32_e32 v16, v79, v79
	v_mul_f32_e32 v83, v75, v75
	v_fmac_f32_e32 v16, v78, v78
	v_fmac_f32_e32 v83, v74, v74
	v_fmac_f32_e32 v16, v80, v80
	v_fmac_f32_e32 v83, v76, v76
	v_fmac_f32_e32 v16, v81, v81
	v_fmac_f32_e32 v83, v77, v77
	v_add_f32_e32 v16, v16, v83
	v_mul_f32_e32 v83, v71, v71
	v_fmac_f32_e32 v83, v70, v70
	v_fmac_f32_e32 v83, v72, v72
	v_fmac_f32_e32 v83, v73, v73
	v_pk_mul_f32 v[110:111], v[66:67], v[66:67]
	v_add_f32_e32 v16, v16, v83
	v_pk_mul_f32 v[108:109], v[68:69], v[68:69]
	v_add_f32_e32 v83, v110, v111
	v_add_f32_e32 v83, v108, v83
	v_add_f32_e32 v83, v109, v83
	v_add_f32_e32 v16, v16, v83
	v_lshl_add_u64 v[108:109], v[98:99], 0, v[90:91]
	s_nop 0
	v_add_f32_dpp v16, v16, v16 quad_perm:[1,0,3,2] row_mask:0xf bank_mask:0xf bound_ctrl:1
	s_nop 1
	v_add_f32_dpp v16, v16, v16 quad_perm:[2,3,0,1] row_mask:0xf bank_mask:0xf bound_ctrl:1
	s_nop 1
	v_add_f32_dpp v16, v16, v16 row_half_mirror row_mask:0xf bank_mask:0xf bound_ctrl:1
	s_nop 1
	v_add_f32_dpp v16, v16, v16 row_mirror row_mask:0xf bank_mask:0xf bound_ctrl:1
	ds_bpermute_b32 v83, v112, v16
	s_waitcnt lgkmcnt(0)
	v_add_f32_e32 v16, v16, v83
	ds_bpermute_b32 v83, v113, v16
	s_waitcnt lgkmcnt(0)
	v_add_f32_e32 v16, v16, v83
	v_fmamk_f32 v16, v16, 0x3a800000, v203
	v_mul_f32_e32 v83, 0x4b800000, v16
	v_cmp_gt_f32_e32 vcc, s16, v16
	s_nop 1
	v_cndmask_b32_e32 v16, v16, v83, vcc
	v_rsq_f32_e32 v16, v16
	s_nop 0
	v_mul_f32_e32 v83, 0x45800000, v16
	v_cndmask_b32_e32 v16, v16, v83, vcc
	v_pk_mul_f32 v[78:79], v[78:79], v[16:17] op_sel_hi:[1,0]
	v_pk_mul_f32 v[80:81], v[80:81], v[16:17] op_sel_hi:[1,0]
	v_pk_mul_f32 v[74:75], v[74:75], v[16:17] op_sel_hi:[1,0]
	v_pk_mul_f32 v[76:77], v[76:77], v[16:17] op_sel_hi:[1,0]
	v_pk_mul_f32 v[70:71], v[70:71], v[16:17] op_sel_hi:[1,0]
	v_pk_mul_f32 v[72:73], v[72:73], v[16:17] op_sel_hi:[1,0]
	v_pk_mul_f32 v[66:67], v[66:67], v[16:17] op_sel_hi:[1,0]
	v_pk_mul_f32 v[68:69], v[68:69], v[16:17] op_sel_hi:[1,0]
	v_pk_mul_f32 v[80:81], v[10:11], v[80:81]
	v_pk_mul_f32 v[78:79], v[8:9], v[78:79]
	v_pk_mul_f32 v[76:77], v[2:3], v[76:77]
	v_pk_mul_f32 v[74:75], v[0:1], v[74:75]
	v_pk_mul_f32 v[72:73], v[6:7], v[72:73]
	v_pk_mul_f32 v[70:71], v[4:5], v[70:71]
	v_pk_mul_f32 v[68:69], v[14:15], v[68:69]
	v_pk_mul_f32 v[66:67], v[12:13], v[66:67]
	v_cvt_pk_f16_f32 v78, v78, v79
	v_cvt_pk_f16_f32 v79, v80, v81
	v_cvt_pk_f16_f32 v74, v74, v75
	v_cvt_pk_f16_f32 v75, v76, v77
	v_cvt_pk_f16_f32 v70, v70, v71
	v_cvt_pk_f16_f32 v71, v72, v73
	v_cvt_pk_f16_f32 v66, v66, v67
	v_cvt_pk_f16_f32 v67, v68, v69
	global_store_dwordx2 v[108:109], v[78:79], off offset:-1024
	global_store_dwordx2 v[108:109], v[74:75], off offset:-512
	global_store_dwordx2 v[108:109], v[70:71], off
	global_store_dwordx2 v[108:109], v[66:67], off offset:512
	s_and_saveexec_b64 s[4:5], s[44:45]
	s_cbranch_execnz .LBB0_766
	s_or_b64 exec, exec, s[4:5]
	s_and_saveexec_b64 s[4:5], s[42:43]
	s_cbranch_execnz .LBB0_772

;     ...
;         for (int b = 0; b < 4; ++b) { const int r = r0 + b * nw;
;             if (r < TT) {
;                 float ss = 0.f;
; #pragma unroll
;                 for (int i = 0; i < 4; ++i) {
;                     if (nsl && r >= TP) {
;                         const float* s = scr + (size_t)(r - TP) * DM + i * 256 + lane * 4;
;                         for (int q = 0; q < nsl; ++q) v[b][i] = v[b][i] + *(const f32x4*)(s + (size_t)q * TS * DM);
;                         if (!final_inplace) *(f32x4*)(X + (size_t)r * DM + i * 256 + lane * 4) = v[b][i]; }
;                     ss += v[b][i][0] * v[b][i][0] + v[b][i][1] * v[b][i][1] + v[b][i][2] * v[b][i][2] + v[b][i][3] * v[b][i][3]; }
.LBB0_766:
	s_waitcnt vmcnt(12)
	v_add_u32_e32 v16, 0xffffc000, v106
	v_lshlrev_b64 v[66:67], 12, v[16:17]
	v_mov_b32_e32 v107, v17
	v_lshl_add_u64 v[68:69], v[84:85], 0, v[66:67]
	v_lshlrev_b64 v[66:67], 12, v[106:107]
	v_cmp_lt_i32_e64 s[44:45], s15, v106
	v_lshl_add_u64 v[66:67], v[86:87], 0, v[66:67]
	s_and_saveexec_b64 s[6:7], s[44:45]
	s_cbranch_execnz .LBB0_782
	s_or_b64 exec, exec, s[6:7]
	s_and_saveexec_b64 s[6:7], s[44:45]
	s_cbranch_execnz .LBB0_783

;     ...
;         for (int b = 0; b < 4; ++b) { const int r = r0 + b * nw;
;             if (r < TT) {
;                 float ss = 0.f;
; #pragma unroll
;                 for (int i = 0; i < 4; ++i) {
;                     if (nsl && r >= TP) {
;                         const float* s = scr + (size_t)(r - TP) * DM + i * 256 + lane * 4;
;                         for (int q = 0; q < nsl; ++q) v[b][i] = v[b][i] + *(const f32x4*)(s + (size_t)q * TS * DM);
;                         if (!final_inplace) *(f32x4*)(X + (size_t)r * DM + i * 256 + lane * 4) = v[b][i]; }
;                     ss += v[b][i][0] * v[b][i][0] + v[b][i][1] * v[b][i][1] + v[b][i][2] * v[b][i][2] + v[b][i][3] * v[b][i][3]; }
.LBB0_772:
	s_waitcnt vmcnt(12)
	v_add_u32_e32 v16, 0xffffc000, v104
	v_lshlrev_b64 v[66:67], 12, v[16:17]
	v_mov_b32_e32 v105, v17
	v_lshl_add_u64 v[68:69], v[84:85], 0, v[66:67]
	v_lshlrev_b64 v[66:67], 12, v[104:105]
	v_cmp_lt_i32_e64 s[42:43], s15, v104
	v_lshl_add_u64 v[66:67], v[86:87], 0, v[66:67]
	s_and_saveexec_b64 s[6:7], s[42:43]
	s_cbranch_execnz .LBB0_785
	s_or_b64 exec, exec, s[6:7]
	s_and_saveexec_b64 s[6:7], s[42:43]
	s_cbranch_execnz .LBB0_786

;     ...
;         for (int b = 0; b < 4; ++b) { const int r = r0 + b * nw;
;             if (r < TT) {
;                 float ss = 0.f;
; #pragma unroll
;                 for (int i = 0; i < 4; ++i) {
;                     if (nsl && r >= TP) {
;                         const float* s = scr + (size_t)(r - TP) * DM + i * 256 + lane * 4;
;                         for (int q = 0; q < nsl; ++q) v[b][i] = v[b][i] + *(const f32x4*)(s + (size_t)q * TS * DM);
;                         if (!final_inplace) *(f32x4*)(X + (size_t)r * DM + i * 256 + lane * 4) = v[b][i]; }
;                     ss += v[b][i][0] * v[b][i][0] + v[b][i][1] * v[b][i][1] + v[b][i][2] * v[b][i][2] + v[b][i][3] * v[b][i][3]; }
.LBB0_778:
	s_waitcnt vmcnt(12)
	v_add_u32_e32 v16, 0xffffc000, v102
	v_lshlrev_b64 v[66:67], 12, v[16:17]
	v_mov_b32_e32 v103, v17
	v_lshl_add_u64 v[68:69], v[84:85], 0, v[66:67]
	v_lshlrev_b64 v[66:67], 12, v[102:103]
	v_cmp_lt_i32_e64 s[40:41], s15, v102
	v_lshl_add_u64 v[66:67], v[86:87], 0, v[66:67]
	s_and_saveexec_b64 s[6:7], s[40:41]
	s_cbranch_execnz .LBB0_788
	s_or_b64 exec, exec, s[6:7]
	s_and_saveexec_b64 s[6:7], s[40:41]
	s_cbranch_execnz .LBB0_789

; __device__ __forceinline__ float red64(float x) { x = red16(x); x += __shfl_xor(x, 16); x += __shfl_xor(x, 32); return x; }
;     ...
;         for (int b = 0; b < 4; ++b) { const int r = r0 + b * nw;
;             if (r < TT) {
;                 float ss = 0.f;
; #pragma unroll
;                 for (int i = 0; i < 4; ++i) {
;                     if (nsl && r >= TP) {
;                         const float* s = scr + (size_t)(r - TP) * DM + i * 256 + lane * 4;
;                         for (int q = 0; q < nsl; ++q) v[b][i] = v[b][i] + *(const f32x4*)(s + (size_t)q * TS * DM);
;                         if (!final_inplace) *(f32x4*)(X + (size_t)r * DM + i * 256 + lane * 4) = v[b][i]; }
;                     ss += v[b][i][0] * v[b][i][0] + v[b][i][1] * v[b][i][1] + v[b][i][2] * v[b][i][2] + v[b][i][3] * v[b][i][3]; }
;                 ss = red64(ss);
;                 const float sc = rsqrtf(ss * (1.0f / DM) + EPS);
; #pragma unroll
;                 for (int i = 0; i < 4; ++i) {
;                     if (srcP && copy_x) *(f32x4*)(X + (size_t)r * DM + i * 256 + lane * 4) = v[b][i];
;                     f32x4 o = v[b][i] * sc * gv[i];
;                     if (final_inplace) *(f32x4*)(X + (size_t)r * DM + i * 256 + lane * 4) = o;
;                     else { u32x2 w; w.x = pkh(o[0], o[1]); w.y = pkh(o[2], o[3]); *(u32x2*)(XN + (size_t)r * DM + i * 256 + lane * 4) = w; }
;                 } } }
.LBB0_1048:
	s_or_b64 exec, exec, s[50:51]
	s_and_b64 s[50:51], s[44:45], s[42:43]
	s_and_b64 s[50:51], s[50:51], s[40:41]
	s_xor_b64 s[50:51], s[50:51], exec
	s_cmp_eq_u64 s[50:51], 0
	s_cbranch_scc1 .Lnw_c
	s_waitcnt vmcnt(0)
.Lnw_c:
	s_waitcnt vmcnt(12)
	v_mov_b32_e32 v100, v79
	v_mov_b32_e32 v101, v75
	v_mov_b32_e32 v96, v78
	v_mov_b32_e32 v97, v74
	v_pk_mul_f32 v[100:101], v[100:101], v[100:101]
	v_mov_b32_e32 v102, v71
	v_pk_fma_f32 v[96:97], v[96:97], v[96:97], v[100:101]
	v_mov_b32_e32 v100, v80
	v_mov_b32_e32 v101, v76
	v_pk_fma_f32 v[96:97], v[100:101], v[100:101], v[96:97]
	v_mov_b32_e32 v100, v81
	v_mov_b32_e32 v101, v77
	v_mov_b32_e32 v103, v67
	v_pk_fma_f32 v[96:97], v[100:101], v[100:101], v[96:97]
	v_mov_b32_e32 v100, v70
	v_mov_b32_e32 v101, v66
	v_pk_mul_f32 v[102:103], v[102:103], v[102:103]
	v_add_f32_e32 v16, v96, v97
	v_pk_fma_f32 v[100:101], v[100:101], v[100:101], v[102:103]
	v_mov_b32_e32 v102, v72
	v_mov_b32_e32 v103, v68
	v_pk_fma_f32 v[100:101], v[102:103], v[102:103], v[100:101]
	v_mov_b32_e32 v102, v73
	v_mov_b32_e32 v103, v69
	v_pk_fma_f32 v[100:101], v[102:103], v[102:103], v[100:101]
	v_lshlrev_b64 v[94:95], 11, v[94:95]
	v_add_f32_e32 v16, v16, v100
	v_add_f32_e32 v16, v16, v101
	v_lshl_add_u64 v[94:95], v[84:85], 0, v[94:95]
	s_nop 0
	v_add_f32_dpp v16, v16, v16 quad_perm:[1,0,3,2] row_mask:0xf bank_mask:0xf bound_ctrl:1
	s_nop 1
	v_add_f32_dpp v16, v16, v16 quad_perm:[2,3,0,1] row_mask:0xf bank_mask:0xf bound_ctrl:1
	s_nop 1
	v_add_f32_dpp v16, v16, v16 row_half_mirror row_mask:0xf bank_mask:0xf bound_ctrl:1
	s_nop 1
	v_add_f32_dpp v16, v16, v16 row_mirror row_mask:0xf bank_mask:0xf bound_ctrl:1
	ds_bpermute_b32 v87, v83, v16
	s_waitcnt lgkmcnt(0)
	v_add_f32_e32 v16, v16, v87
	ds_bpermute_b32 v87, v98, v16
	s_waitcnt lgkmcnt(0)
	v_add_f32_e32 v16, v16, v87
	v_fmamk_f32 v16, v16, 0x3a800000, v203
	v_mul_f32_e32 v87, 0x4b800000, v16
	v_cmp_gt_f32_e32 vcc, s16, v16
	s_nop 1
	v_cndmask_b32_e32 v16, v16, v87, vcc
	v_rsq_f32_e32 v16, v16
	s_nop 0
	v_mul_f32_e32 v87, 0x45800000, v16
	v_cndmask_b32_e32 v16, v16, v87, vcc
	v_pk_mul_f32 v[78:79], v[78:79], v[16:17] op_sel_hi:[1,0]
	v_pk_mul_f32 v[80:81], v[80:81], v[16:17] op_sel_hi:[1,0]
	v_pk_mul_f32 v[74:75], v[74:75], v[16:17] op_sel_hi:[1,0]
	v_pk_mul_f32 v[76:77], v[76:77], v[16:17] op_sel_hi:[1,0]
	v_pk_mul_f32 v[70:71], v[70:71], v[16:17] op_sel_hi:[1,0]
	v_pk_mul_f32 v[72:73], v[72:73], v[16:17] op_sel_hi:[1,0]
	v_pk_mul_f32 v[66:67], v[66:67], v[16:17] op_sel_hi:[1,0]
	v_pk_mul_f32 v[68:69], v[68:69], v[16:17] op_sel_hi:[1,0]
	v_pk_mul_f32 v[80:81], v[2:3], v[80:81]
	v_pk_mul_f32 v[78:79], v[0:1], v[78:79]
	v_pk_mul_f32 v[76:77], v[6:7], v[76:77]
	v_pk_mul_f32 v[74:75], v[4:5], v[74:75]
	v_pk_mul_f32 v[72:73], v[10:11], v[72:73]
	v_pk_mul_f32 v[70:71], v[8:9], v[70:71]
	v_pk_mul_f32 v[68:69], v[14:15], v[68:69]
	v_pk_mul_f32 v[66:67], v[12:13], v[66:67]
	v_cvt_pk_f16_f32 v78, v78, v79
	v_cvt_pk_f16_f32 v79, v80, v81
	v_cvt_pk_f16_f32 v74, v74, v75
	v_cvt_pk_f16_f32 v75, v76, v77
	v_cvt_pk_f16_f32 v70, v70, v71
	v_cvt_pk_f16_f32 v71, v72, v73
	v_cvt_pk_f16_f32 v66, v66, v67
	v_cvt_pk_f16_f32 v67, v68, v69
	global_store_dwordx2 v[94:95], v[78:79], off
	global_store_dwordx2 v[94:95], v[74:75], off offset:512
	global_store_dwordx2 v[94:95], v[70:71], off offset:1024
	global_store_dwordx2 v[94:95], v[66:67], off offset:1536
	s_and_saveexec_b64 s[46:47], s[44:45]
	s_cbranch_execnz .LBB0_1051
	s_or_b64 exec, exec, s[46:47]
	s_and_saveexec_b64 s[44:45], s[42:43]
	s_cbranch_execnz .LBB0_1052

; __device__ __forceinline__ float red64(float x) { x = red16(x); x += __shfl_xor(x, 16); x += __shfl_xor(x, 32); return x; }
;     ...
;         for (int b = 0; b < 4; ++b) { const int r = r0 + b * nw;
;             if (r < TT) {
;                 float ss = 0.f;
; #pragma unroll
;                 for (int i = 0; i < 4; ++i) {
;                     if (nsl && r >= TP) {
;                         const float* s = scr + (size_t)(r - TP) * DM + i * 256 + lane * 4;
;                         for (int q = 0; q < nsl; ++q) v[b][i] = v[b][i] + *(const f32x4*)(s + (size_t)q * TS * DM);
;                         if (!final_inplace) *(f32x4*)(X + (size_t)r * DM + i * 256 + lane * 4) = v[b][i]; }
;                     ss += v[b][i][0] * v[b][i][0] + v[b][i][1] * v[b][i][1] + v[b][i][2] * v[b][i][2] + v[b][i][3] * v[b][i][3]; }
;                 ss = red64(ss);
;                 const float sc = rsqrtf(ss * (1.0f / DM) + EPS);
; #pragma unroll
;                 for (int i = 0; i < 4; ++i) {
;                     if (srcP && copy_x) *(f32x4*)(X + (size_t)r * DM + i * 256 + lane * 4) = v[b][i];
;                     f32x4 o = v[b][i] * sc * gv[i];
;                     if (final_inplace) *(f32x4*)(X + (size_t)r * DM + i * 256 + lane * 4) = o;
;                     else { u32x2 w; w.x = pkh(o[0], o[1]); w.y = pkh(o[2], o[3]); *(u32x2*)(XN + (size_t)r * DM + i * 256 + lane * 4) = w; }
;                 } } }
.LBB0_1051:
	s_waitcnt vmcnt(12)
	v_mov_b32_e32 v68, v55
	v_mov_b32_e32 v69, v51
	v_mov_b32_e32 v66, v54
	v_mov_b32_e32 v67, v50
	v_pk_mul_f32 v[68:69], v[68:69], v[68:69]
	v_mov_b32_e32 v70, v63
	v_pk_fma_f32 v[66:67], v[66:67], v[66:67], v[68:69]
	v_mov_b32_e32 v68, v56
	v_mov_b32_e32 v69, v52
	v_pk_fma_f32 v[66:67], v[68:69], v[68:69], v[66:67]
	v_mov_b32_e32 v68, v57
	v_mov_b32_e32 v69, v53
	v_mov_b32_e32 v71, v59
	v_pk_fma_f32 v[66:67], v[68:69], v[68:69], v[66:67]
	v_mov_b32_e32 v68, v62
	v_mov_b32_e32 v69, v58
	v_pk_mul_f32 v[70:71], v[70:71], v[70:71]
	v_add_f32_e32 v16, v66, v67
	v_pk_fma_f32 v[68:69], v[68:69], v[68:69], v[70:71]
	v_mov_b32_e32 v70, v64
	v_mov_b32_e32 v71, v60
	v_pk_fma_f32 v[68:69], v[70:71], v[70:71], v[68:69]
	v_mov_b32_e32 v70, v65
	v_mov_b32_e32 v71, v61
	v_pk_fma_f32 v[68:69], v[70:71], v[70:71], v[68:69]
	v_ashrrev_i32_e32 v93, 31, v92
	v_add_f32_e32 v16, v69, v16
	v_add_f32_e32 v16, v68, v16
	s_nop 1
	v_add_f32_dpp v16, v16, v16 quad_perm:[1,0,3,2] row_mask:0xf bank_mask:0xf bound_ctrl:1
	s_nop 1
	v_add_f32_dpp v16, v16, v16 quad_perm:[2,3,0,1] row_mask:0xf bank_mask:0xf bound_ctrl:1
	s_nop 1
	v_add_f32_dpp v16, v16, v16 row_half_mirror row_mask:0xf bank_mask:0xf bound_ctrl:1
	s_nop 1
	v_add_f32_dpp v16, v16, v16 row_mirror row_mask:0xf bank_mask:0xf bound_ctrl:1
	ds_bpermute_b32 v66, v83, v16
	s_waitcnt lgkmcnt(0)
	v_add_f32_e32 v16, v16, v66
	ds_bpermute_b32 v66, v98, v16
	s_waitcnt lgkmcnt(0)
	v_add_f32_e32 v16, v16, v66
	v_fmamk_f32 v16, v16, 0x3a800000, v203
	v_mul_f32_e32 v66, 0x4b800000, v16
	v_cmp_gt_f32_e32 vcc, s16, v16
	s_nop 1
	v_cndmask_b32_e32 v16, v16, v66, vcc
	v_rsq_f32_e32 v16, v16
	s_nop 0
	v_mul_f32_e32 v66, 0x45800000, v16
	v_cndmask_b32_e32 v16, v16, v66, vcc
	v_pk_mul_f32 v[68:69], v[50:51], v[16:17] op_sel_hi:[1,0]
	v_pk_mul_f32 v[70:71], v[52:53], v[16:17] op_sel_hi:[1,0]
	v_lshlrev_b64 v[66:67], 11, v[92:93]
	v_pk_mul_f32 v[70:71], v[2:3], v[70:71]
	v_pk_mul_f32 v[68:69], v[0:1], v[68:69]
	v_lshl_add_u64 v[66:67], v[84:85], 0, v[66:67]
	v_cvt_pk_f16_f32 v68, v68, v69
	v_cvt_pk_f16_f32 v69, v70, v71
	global_store_dwordx2 v[66:67], v[68:69], off
	v_pk_mul_f32 v[68:69], v[54:55], v[16:17] op_sel_hi:[1,0]
	v_pk_mul_f32 v[70:71], v[56:57], v[16:17] op_sel_hi:[1,0]
	v_pk_mul_f32 v[68:69], v[4:5], v[68:69]
	v_pk_mul_f32 v[70:71], v[6:7], v[70:71]
	v_cvt_pk_f16_f32 v68, v68, v69
	v_cvt_pk_f16_f32 v69, v70, v71
	global_store_dwordx2 v[66:67], v[68:69], off offset:512
	v_pk_mul_f32 v[68:69], v[58:59], v[16:17] op_sel_hi:[1,0]
	v_pk_mul_f32 v[70:71], v[60:61], v[16:17] op_sel_hi:[1,0]
	v_pk_mul_f32 v[68:69], v[8:9], v[68:69]
	v_pk_mul_f32 v[70:71], v[10:11], v[70:71]
	v_cvt_pk_f16_f32 v68, v68, v69
	v_cvt_pk_f16_f32 v69, v70, v71
	global_store_dwordx2 v[66:67], v[68:69], off offset:1024
	v_pk_mul_f32 v[68:69], v[62:63], v[16:17] op_sel_hi:[1,0]
	v_pk_mul_f32 v[70:71], v[64:65], v[16:17] op_sel_hi:[1,0]
	v_pk_mul_f32 v[68:69], v[12:13], v[68:69]
	v_pk_mul_f32 v[70:71], v[14:15], v[70:71]
	v_cvt_pk_f16_f32 v68, v68, v69
	v_cvt_pk_f16_f32 v69, v70, v71
	global_store_dwordx2 v[66:67], v[68:69], off offset:1536
	s_or_b64 exec, exec, s[46:47]
	s_and_saveexec_b64 s[44:45], s[42:43]
	s_cbranch_execz .LBB0_1050
; __device__ __forceinline__ float red64(float x) { x = red16(x); x += __shfl_xor(x, 16); x += __shfl_xor(x, 32); return x; }
;     ...
;         for (int b = 0; b < 4; ++b) { const int r = r0 + b * nw;
;             if (r < TT) {
;                 float ss = 0.f;
; #pragma unroll
;                 for (int i = 0; i < 4; ++i) {
;                     if (nsl && r >= TP) {
;                         const float* s = scr + (size_t)(r - TP) * DM + i * 256 + lane * 4;
;                         for (int q = 0; q < nsl; ++q) v[b][i] = v[b][i] + *(const f32x4*)(s + (size_t)q * TS * DM);
;                         if (!final_inplace) *(f32x4*)(X + (size_t)r * DM + i * 256 + lane * 4) = v[b][i]; }
;                     ss += v[b][i][0] * v[b][i][0] + v[b][i][1] * v[b][i][1] + v[b][i][2] * v[b][i][2] + v[b][i][3] * v[b][i][3]; }
;                 ss = red64(ss);
;                 const float sc = rsqrtf(ss * (1.0f / DM) + EPS);
; #pragma unroll
;                 for (int i = 0; i < 4; ++i) {
;                     if (srcP && copy_x) *(f32x4*)(X + (size_t)r * DM + i * 256 + lane * 4) = v[b][i];
;                     f32x4 o = v[b][i] * sc * gv[i];
;                     if (final_inplace) *(f32x4*)(X + (size_t)r * DM + i * 256 + lane * 4) = o;
;                     else { u32x2 w; w.x = pkh(o[0], o[1]); w.y = pkh(o[2], o[3]); *(u32x2*)(XN + (size_t)r * DM + i * 256 + lane * 4) = w; }
;                 } } }
.LBB0_1052:
	s_waitcnt vmcnt(12)
	v_mov_b32_e32 v68, v43
	v_mov_b32_e32 v69, v47
	v_mov_b32_e32 v66, v42
	v_mov_b32_e32 v67, v46
	v_pk_mul_f32 v[68:69], v[68:69], v[68:69]
	v_mov_b32_e32 v70, v35
	v_pk_fma_f32 v[66:67], v[66:67], v[66:67], v[68:69]
	v_mov_b32_e32 v68, v44
	v_mov_b32_e32 v69, v48
	v_pk_fma_f32 v[66:67], v[68:69], v[68:69], v[66:67]
	v_mov_b32_e32 v68, v45
	v_mov_b32_e32 v69, v49
	v_mov_b32_e32 v71, v39
	v_pk_fma_f32 v[66:67], v[68:69], v[68:69], v[66:67]
	v_mov_b32_e32 v68, v34
	v_mov_b32_e32 v69, v38
	v_pk_mul_f32 v[70:71], v[70:71], v[70:71]
	v_add_f32_e32 v16, v66, v67
	v_pk_fma_f32 v[68:69], v[68:69], v[68:69], v[70:71]
	v_mov_b32_e32 v70, v36
	v_mov_b32_e32 v71, v40
	v_pk_fma_f32 v[68:69], v[70:71], v[70:71], v[68:69]
	v_mov_b32_e32 v70, v37
	v_mov_b32_e32 v71, v41
	v_pk_fma_f32 v[68:69], v[70:71], v[70:71], v[68:69]
	v_ashrrev_i32_e32 v91, 31, v90
	v_add_f32_e32 v16, v69, v16
	v_add_f32_e32 v16, v68, v16
	s_nop 1
	v_add_f32_dpp v16, v16, v16 quad_perm:[1,0,3,2] row_mask:0xf bank_mask:0xf bound_ctrl:1
	s_nop 1
	v_add_f32_dpp v16, v16, v16 quad_perm:[2,3,0,1] row_mask:0xf bank_mask:0xf bound_ctrl:1
	s_nop 1
	v_add_f32_dpp v16, v16, v16 row_half_mirror row_mask:0xf bank_mask:0xf bound_ctrl:1
	s_nop 1
	v_add_f32_dpp v16, v16, v16 row_mirror row_mask:0xf bank_mask:0xf bound_ctrl:1
	ds_bpermute_b32 v66, v83, v16
	s_waitcnt lgkmcnt(0)
	v_add_f32_e32 v16, v16, v66
	ds_bpermute_b32 v66, v98, v16
	s_waitcnt lgkmcnt(0)
	v_add_f32_e32 v16, v16, v66
	v_fmamk_f32 v16, v16, 0x3a800000, v203
	v_mul_f32_e32 v66, 0x4b800000, v16
	v_cmp_gt_f32_e32 vcc, s16, v16
	s_nop 1
	v_cndmask_b32_e32 v16, v16, v66, vcc
	v_rsq_f32_e32 v16, v16
	s_nop 0
	v_mul_f32_e32 v66, 0x45800000, v16
	v_cndmask_b32_e32 v16, v16, v66, vcc
	v_pk_mul_f32 v[68:69], v[46:47], v[16:17] op_sel_hi:[1,0]
	v_pk_mul_f32 v[70:71], v[48:49], v[16:17] op_sel_hi:[1,0]
	v_lshlrev_b64 v[66:67], 11, v[90:91]
	v_pk_mul_f32 v[70:71], v[2:3], v[70:71]
	v_pk_mul_f32 v[68:69], v[0:1], v[68:69]
	v_lshl_add_u64 v[66:67], v[84:85], 0, v[66:67]
	v_cvt_pk_f16_f32 v68, v68, v69
	v_cvt_pk_f16_f32 v69, v70, v71
	global_store_dwordx2 v[66:67], v[68:69], off
	v_pk_mul_f32 v[68:69], v[42:43], v[16:17] op_sel_hi:[1,0]
	v_pk_mul_f32 v[70:71], v[44:45], v[16:17] op_sel_hi:[1,0]
	v_pk_mul_f32 v[68:69], v[4:5], v[68:69]
	v_pk_mul_f32 v[70:71], v[6:7], v[70:71]
	v_cvt_pk_f16_f32 v68, v68, v69
	v_cvt_pk_f16_f32 v69, v70, v71
	global_store_dwordx2 v[66:67], v[68:69], off offset:512
	v_pk_mul_f32 v[68:69], v[38:39], v[16:17] op_sel_hi:[1,0]
	v_pk_mul_f32 v[70:71], v[40:41], v[16:17] op_sel_hi:[1,0]
	v_pk_mul_f32 v[68:69], v[8:9], v[68:69]
	v_pk_mul_f32 v[70:71], v[10:11], v[70:71]
	v_cvt_pk_f16_f32 v68, v68, v69
	v_cvt_pk_f16_f32 v69, v70, v71
	global_store_dwordx2 v[66:67], v[68:69], off offset:1024
	v_pk_mul_f32 v[68:69], v[34:35], v[16:17] op_sel_hi:[1,0]
	v_pk_mul_f32 v[70:71], v[36:37], v[16:17] op_sel_hi:[1,0]
	v_pk_mul_f32 v[68:69], v[12:13], v[68:69]
	v_pk_mul_f32 v[70:71], v[14:15], v[70:71]
	v_cvt_pk_f16_f32 v68, v68, v69
	v_cvt_pk_f16_f32 v69, v70, v71
	global_store_dwordx2 v[66:67], v[68:69], off offset:1536
	s_or_b64 exec, exec, s[44:45]
	s_and_saveexec_b64 s[42:43], s[40:41]
	s_cbranch_execz .LBB0_1013
.LBB0_1053:
	s_waitcnt vmcnt(12)
	v_mov_b32_e32 v68, v27
	v_mov_b32_e32 v69, v31
	v_mov_b32_e32 v66, v26
	v_mov_b32_e32 v67, v30
	v_pk_mul_f32 v[68:69], v[68:69], v[68:69]
	v_mov_b32_e32 v70, v19
	v_pk_fma_f32 v[66:67], v[66:67], v[66:67], v[68:69]
	v_mov_b32_e32 v68, v28
	v_mov_b32_e32 v69, v32
	v_pk_fma_f32 v[66:67], v[68:69], v[68:69], v[66:67]
	v_mov_b32_e32 v68, v29
	v_mov_b32_e32 v69, v33
	v_mov_b32_e32 v71, v23
	v_pk_fma_f32 v[66:67], v[68:69], v[68:69], v[66:67]
	v_mov_b32_e32 v68, v18
	v_mov_b32_e32 v69, v22
	v_pk_mul_f32 v[70:71], v[70:71], v[70:71]
	v_add_f32_e32 v16, v66, v67
	v_pk_fma_f32 v[68:69], v[68:69], v[68:69], v[70:71]
	v_mov_b32_e32 v70, v20
	v_mov_b32_e32 v71, v24
	v_pk_fma_f32 v[68:69], v[70:71], v[70:71], v[68:69]
	v_mov_b32_e32 v70, v21
	v_mov_b32_e32 v71, v25
	v_pk_fma_f32 v[68:69], v[70:71], v[70:71], v[68:69]
	v_ashrrev_i32_e32 v89, 31, v88
	v_add_f32_e32 v16, v69, v16
	v_add_f32_e32 v16, v68, v16
	s_nop 1
	v_add_f32_dpp v16, v16, v16 quad_perm:[1,0,3,2] row_mask:0xf bank_mask:0xf bound_ctrl:1
	s_nop 1
	v_add_f32_dpp v16, v16, v16 quad_perm:[2,3,0,1] row_mask:0xf bank_mask:0xf bound_ctrl:1
	s_nop 1
	v_add_f32_dpp v16, v16, v16 row_half_mirror row_mask:0xf bank_mask:0xf bound_ctrl:1
	s_nop 1
	v_add_f32_dpp v16, v16, v16 row_mirror row_mask:0xf bank_mask:0xf bound_ctrl:1
	ds_bpermute_b32 v66, v83, v16
	s_waitcnt lgkmcnt(0)
	v_add_f32_e32 v16, v16, v66
	ds_bpermute_b32 v66, v98, v16
	s_waitcnt lgkmcnt(0)
	v_add_f32_e32 v16, v16, v66
	v_fmamk_f32 v16, v16, 0x3a800000, v203
	v_mul_f32_e32 v66, 0x4b800000, v16
	v_cmp_gt_f32_e32 vcc, s16, v16
	s_nop 1
	v_cndmask_b32_e32 v16, v16, v66, vcc
	v_rsq_f32_e32 v16, v16
	s_nop 0
	v_mul_f32_e32 v66, 0x45800000, v16
	v_cndmask_b32_e32 v16, v16, v66, vcc
	v_pk_mul_f32 v[68:69], v[30:31], v[16:17] op_sel_hi:[1,0]
	v_pk_mul_f32 v[70:71], v[32:33], v[16:17] op_sel_hi:[1,0]
	v_lshlrev_b64 v[66:67], 11, v[88:89]
	v_pk_mul_f32 v[70:71], v[2:3], v[70:71]
	v_pk_mul_f32 v[68:69], v[0:1], v[68:69]
	v_lshl_add_u64 v[66:67], v[84:85], 0, v[66:67]
	v_cvt_pk_f16_f32 v68, v68, v69
	v_cvt_pk_f16_f32 v69, v70, v71
	global_store_dwordx2 v[66:67], v[68:69], off
	v_pk_mul_f32 v[68:69], v[26:27], v[16:17] op_sel_hi:[1,0]
	v_pk_mul_f32 v[70:71], v[28:29], v[16:17] op_sel_hi:[1,0]
	v_pk_mul_f32 v[68:69], v[4:5], v[68:69]
	v_pk_mul_f32 v[70:71], v[6:7], v[70:71]
	v_cvt_pk_f16_f32 v68, v68, v69
	v_cvt_pk_f16_f32 v69, v70, v71
	global_store_dwordx2 v[66:67], v[68:69], off offset:512
	v_pk_mul_f32 v[68:69], v[22:23], v[16:17] op_sel_hi:[1,0]
	v_pk_mul_f32 v[70:71], v[24:25], v[16:17] op_sel_hi:[1,0]
	v_pk_mul_f32 v[68:69], v[8:9], v[68:69]
	v_pk_mul_f32 v[70:71], v[10:11], v[70:71]
	v_cvt_pk_f16_f32 v68, v68, v69
	v_cvt_pk_f16_f32 v69, v70, v71
	global_store_dwordx2 v[66:67], v[68:69], off offset:1024
	v_pk_mul_f32 v[68:69], v[18:19], v[16:17] op_sel_hi:[1,0]
	v_pk_mul_f32 v[70:71], v[20:21], v[16:17] op_sel_hi:[1,0]
	v_pk_mul_f32 v[68:69], v[12:13], v[68:69]
	v_pk_mul_f32 v[70:71], v[14:15], v[70:71]
	v_cvt_pk_f16_f32 v68, v68, v69
	v_cvt_pk_f16_f32 v69, v70, v71
	global_store_dwordx2 v[66:67], v[68:69], off offset:1536
	s_branch .LBB0_1013
